# scan loop: all q/aa loads issued after the MFMAs (none at iteration top), waits 13/10
# speedup vs baseline: 1.0073x; 1.0073x over previous
; #define LAS __attribute__((address_space(3)))
; DI void scan_load(ScanFrags& F, const unsigned char* ws, int c, int h, int dir, int sl, int w, int lane) {
;     const size_t blk = (size_t)((c * 4 + h) * 2 + dir);
;     const bf16_t* QT = (const bf16_t*)(ws + WS_U) + blk * 16384 + lane * 8;
;     const bf16_t* KH = (const bf16_t*)(ws + WS_KH) + blk * 16384 + lane * 8;
;     const bf16_t* AM = (const bf16_t*)(ws + WS_AM) + blk * 4096 + lane * 8;
; #pragma unroll
;     for (int mb = 0; mb < 2; ++mb)
; #pragma unroll
;         for (int s = 0; s < 2; ++s) F.qa[mb][s] = *(const bf16x8*)(QT + ((w * 2 + mb) * 2 + s) * 512);
; #pragma unroll
;     for (int s = 0; s < 4; ++s) F.ka[s] = *(const bf16x8*)(KH + (w * 4 + s) * 512);
; #pragma unroll
;     for (int mb = 0; mb < 2; ++mb) F.aa[mb] = w < 4 ? *(const bf16x8*)(AM + ((w * 2 + mb)) * 512) : (bf16x8){0, 0, 0, 0, 0, 0, 0, 0};
; DI void phase_scan(const Params& p, LAS unsigned char* lds, unsigned char* ldsg, int j, int conv_rows, int next_layer) {
;     ...
;             const int c = scan_chunk(n, b, dir);
;             scan_load(nn, p.ws, scan_chunk(n < 258 ? n + 2 : 259, b, dir), h, dir, sl, w, lane);
;             const bf16x8 sb0 = pack8(S, 0), sb1 = pack8(S, 1);
;             bf16x8 vb[4]; f32x4 dd[4];
;             {
;                 unsigned vo = (unsigned)(SCAN_VB_OFF + (n & 1) * 4096 + lane * 16), dofs = (unsigned)(SCAN_DD_OFF + (n & 1) * 1024 + (32 * w + 4 * hh) * 4);
;                 asm volatile("" : "+v"(vo), "+v"(dofs));
; #pragma unroll
;                 for (int s = 0; s < 4; ++s) { vb[s] = *(const LAS bf16x8*)(lds + vo + s * 1024); dd[s] = *(const LAS f32x4*)(lds + dofs + s * 32); }
;             }
;             const bf16x8 vw = (w & 3) == 0 ? vb[0] : ((w & 3) == 1 ? vb[1] : ((w & 3) == 2 ? vb[2] : vb[3]));
.LBB0_536:
.Lscp0_top_a:
	s_add_i32 s58, s57, -1
	s_min_u32 s34, s58, 0x101
	s_add_i32 s36, s34, -2
	s_sub_i32 s37, 0x101, s34
	s_and_b64 s[34:35], s[30:31], exec
	s_cselect_b32 s34, s36, s37
	s_add_i32 s34, s34, s56
	s_lshl_b32 s34, s34, 2
	s_or_b32 s34, s34, s54
	s_mov_b32 s88, s34
	s_ashr_i32 s89, s34, 31
	s_lshl_b64 s[88:89], s[88:89], 15
	s_lshl_b32 s35, s34, 1
	s_or_b32 s36, s35, s55
	s_ashr_i32 s37, s36, 31
	s_lshl_b64 s[86:87], s[36:37], 10
	s_lshl_b64 s[38:39], s[36:37], 15
	v_lshl_add_u64 v[52:53], v[220:221], 0, s[38:39]
	v_lshl_add_u64 v[54:55], v[222:223], 0, s[38:39]
	s_lshl_b64 s[90:91], s[36:37], 13
	v_lshl_add_u64 v[216:217], v[226:227], 0, s[90:91]
	v_mov_b32_e32 v164, v50
	v_mov_b32_e32 v165, v50
	v_mov_b32_e32 v166, v50
	v_mov_b32_e32 v167, v50
	v_mov_b32_e32 v172, v50
	v_mov_b32_e32 v173, v50
	v_mov_b32_e32 v174, v50
	v_mov_b32_e32 v175, v50
	s_and_b32 s38, s58, 1
	v_lshl_or_b32 v18, s38, 12, v238
	v_lshl_add_u32 v19, s38, 10, v239
	v_cmp_lt_i32_e32 vcc, 0, v240
	v_add_u32_e32 v19, 0, v19
	v_add_u32_e32 v18, 0, v18
	ds_read_b128 v[200:203], v19
	ds_read_b128 v[196:199], v19 offset:32
	ds_read_b128 v[192:195], v18
	ds_read_b128 v[188:191], v18 offset:1024
	ds_read_b128 v[184:187], v18 offset:2048
	ds_read_b128 v[180:183], v18 offset:3072
	ds_read_b128 v[204:207], v19 offset:64
	ds_read_b128 v[208:211], v19 offset:96
	s_waitcnt lgkmcnt(5)
	v_mov_b64_e32 v[214:215], v[194:195]
	v_mov_b64_e32 v[212:213], v[192:193]
	s_and_saveexec_b64 s[34:35], vcc
	s_cbranch_execz .Lscp0_a_550
	v_cmp_ne_u32_e32 vcc, 1, v240
	s_and_saveexec_b64 s[36:37], vcc
	s_xor_b64 s[36:37], exec, s[36:37]
	s_cbranch_execz .Lscp0_a_547
	s_waitcnt lgkmcnt(2)
	v_cndmask_b32_e64 v215, v183, v187, s[12:13]
	v_cndmask_b32_e64 v214, v182, v186, s[12:13]
	v_cndmask_b32_e64 v213, v181, v185, s[12:13]
	v_cndmask_b32_e64 v212, v180, v184, s[12:13]

; #define LAS __attribute__((address_space(3)))
; DI void scan_load(ScanFrags& F, const unsigned char* ws, int c, int h, int dir, int sl, int w, int lane) {
;     ...
;         for (int s = 0; s < 2; ++s) F.qa[mb][s] = *(const bf16x8*)(QT + ((w * 2 + mb) * 2 + s) * 512);
; #pragma unroll
;     for (int s = 0; s < 4; ++s) F.ka[s] = *(const bf16x8*)(KH + (w * 4 + s) * 512);
; #pragma unroll
;     for (int mb = 0; mb < 2; ++mb) F.aa[mb] = w < 4 ? *(const bf16x8*)(AM + ((w * 2 + mb)) * 512) : (bf16x8){0, 0, 0, 0, 0, 0, 0, 0};
; DI void phase_scan(const Params& p, LAS unsigned char* lds, unsigned char* ldsg, int j, int conv_rows, int next_layer) {
;     ...
;             const bf16x8 sb0 = pack8(S, 0), sb1 = pack8(S, 1);
;             bf16x8 vb[4]; f32x4 dd[4];
;             {
;                 unsigned vo = (unsigned)(SCAN_VB_OFF + (n & 1) * 4096 + lane * 16), dofs = (unsigned)(SCAN_DD_OFF + (n & 1) * 1024 + (32 * w + 4 * hh) * 4);
;                 asm volatile("" : "+v"(vo), "+v"(dofs));
; #pragma unroll
;                 for (int s = 0; s < 4; ++s) { vb[s] = *(const LAS bf16x8*)(lds + vo + s * 1024); dd[s] = *(const LAS f32x4*)(lds + dofs + s * 32); }
;             }
;             const bf16x8 vw = (w & 3) == 0 ? vb[0] : ((w & 3) == 1 ? vb[1] : ((w & 3) == 2 ? vb[2] : vb[3]));
;             bf16x8 aa0 = cur.aa[0], aa1 = cur.aa[1];
;             unsigned rbo = (unsigned)(((n & 1) * 8 + w) * 4608 + r * 72 + hh * 8);
;             asm volatile("" : "+v"(rbo));
;             LAS unsigned char* rb = lds + rbo;
; #pragma unroll
;             for (int mb = 0; mb < 2; ++mb) {
;                 f32x16 o;
; #pragma unroll
;                 for (int i = 0; i < 16; ++i) o[i] = 0.f;
;                 o = __builtin_amdgcn_mfma_f32_32x32x16_bf16(sb0, cur.qa[mb][0], o, 0, 0, 0);
;                 o = __builtin_amdgcn_mfma_f32_32x32x16_bf16(sb1, cur.qa[mb][1], o, 0, 0, 0);
;                 o = __builtin_amdgcn_mfma_f32_32x32x16_bf16(vw, mb ? aa1 : aa0, o, 0, 0, 0);
.Lscp0_a_550:
	s_or_b64 exec, exec, s[34:35]
	s_cmp_lg_u64 s[4:5], 0
	s_cbranch_scc1 .Lw1a_p0a
	s_waitcnt vmcnt(10)
	s_branch .Lw1b_p0a
.Lw1a_p0a:
	s_waitcnt vmcnt(13)
.Lw1b_p0a:
	v_cvt_pk_bf16_f32 v34, v2, v3
	v_cvt_pk_bf16_f32 v35, v4, v5
	v_cvt_pk_bf16_f32 v36, v6, v7
	v_cvt_pk_bf16_f32 v37, v8, v9
	v_cvt_pk_bf16_f32 v250, v10, v11
	v_cvt_pk_bf16_f32 v251, v12, v13
	v_mfma_f32_32x32x16_bf16 v[18:33], v[34:37], v[120:123], 0
	v_cvt_pk_bf16_f32 v252, v14, v15
	v_cvt_pk_bf16_f32 v253, v16, v17
	v_lshl_add_u32 v51, s38, 3, v1
	v_mad_u32_u24 v51, v51, s51, v241
	s_and_b32 s39, s57, 1
	v_add_u32_e32 v51, 0, v51
	v_mfma_f32_32x32x16_bf16 v[34:49], v[34:37], v[108:111], 0
	v_mfma_f32_32x32x16_bf16 v[18:33], v[250:253], v[116:119], v[18:33]
	v_mfma_f32_32x32x16_bf16 v[34:49], v[250:253], v[104:107], v[34:49]
	v_mfma_f32_32x32x16_bf16 v[18:33], v[212:215], v[124:127], v[18:33]
	v_mfma_f32_32x32x16_bf16 v[34:49], v[212:215], v[112:115], v[34:49]
	global_load_dwordx4 v[76:79], v[52:53], off
	global_load_dwordx4 v[84:87], v[52:53], off offset:1024
	global_load_dwordx4 v[92:95], v[52:53], off offset:2048
	global_load_dwordx4 v[100:103], v[52:53], off offset:3072
	s_and_saveexec_b64 s[92:93], s[4:5]
	s_cbranch_execz .Laask_p0a
	global_load_dwordx4 v[164:167], v[216:217], off
	global_load_dwordx4 v[172:175], v[216:217], off offset:1024

; #define LAS __attribute__((address_space(3)))
; DI void scan_load(ScanFrags& F, const unsigned char* ws, int c, int h, int dir, int sl, int w, int lane) {
;     const size_t blk = (size_t)((c * 4 + h) * 2 + dir);
;     const bf16_t* QT = (const bf16_t*)(ws + WS_U) + blk * 16384 + lane * 8;
;     const bf16_t* KH = (const bf16_t*)(ws + WS_KH) + blk * 16384 + lane * 8;
;     const bf16_t* AM = (const bf16_t*)(ws + WS_AM) + blk * 4096 + lane * 8;
; #pragma unroll
;     for (int mb = 0; mb < 2; ++mb)
; #pragma unroll
;         for (int s = 0; s < 2; ++s) F.qa[mb][s] = *(const bf16x8*)(QT + ((w * 2 + mb) * 2 + s) * 512);
; #pragma unroll
;     for (int s = 0; s < 4; ++s) F.ka[s] = *(const bf16x8*)(KH + (w * 4 + s) * 512);
; #pragma unroll
;     for (int mb = 0; mb < 2; ++mb) F.aa[mb] = w < 4 ? *(const bf16x8*)(AM + ((w * 2 + mb)) * 512) : (bf16x8){0, 0, 0, 0, 0, 0, 0, 0};
; DI void phase_scan(const Params& p, LAS unsigned char* lds, unsigned char* ldsg, int j, int conv_rows, int next_layer) {
;     ...
;             const int c = scan_chunk(n, b, dir);
;             scan_load(nn, p.ws, scan_chunk(n < 258 ? n + 2 : 259, b, dir), h, dir, sl, w, lane);
;             const bf16x8 sb0 = pack8(S, 0), sb1 = pack8(S, 1);
;             bf16x8 vb[4]; f32x4 dd[4];
;             {
;                 unsigned vo = (unsigned)(SCAN_VB_OFF + (n & 1) * 4096 + lane * 16), dofs = (unsigned)(SCAN_DD_OFF + (n & 1) * 1024 + (32 * w + 4 * hh) * 4);
;                 asm volatile("" : "+v"(vo), "+v"(dofs));
; #pragma unroll
;                 for (int s = 0; s < 4; ++s) { vb[s] = *(const LAS bf16x8*)(lds + vo + s * 1024); dd[s] = *(const LAS f32x4*)(lds + dofs + s * 32); }
;             }
;             const bf16x8 vw = (w & 3) == 0 ? vb[0] : ((w & 3) == 1 ? vb[1] : ((w & 3) == 2 ? vb[2] : vb[3]));
.Lscp0_top_b:
	s_add_i32 s58, s57, -1
	s_min_u32 s34, s58, 0x101
	s_add_i32 s36, s34, -2
	s_sub_i32 s37, 0x101, s34
	s_and_b64 s[34:35], s[30:31], exec
	s_cselect_b32 s34, s36, s37
	s_add_i32 s34, s34, s56
	s_lshl_b32 s34, s34, 2
	s_or_b32 s34, s34, s54
	s_mov_b32 s88, s34
	s_ashr_i32 s89, s34, 31
	s_lshl_b64 s[88:89], s[88:89], 15
	s_lshl_b32 s35, s34, 1
	s_or_b32 s36, s35, s55
	s_ashr_i32 s37, s36, 31
	s_lshl_b64 s[86:87], s[36:37], 10
	s_lshl_b64 s[38:39], s[36:37], 15
	v_lshl_add_u64 v[52:53], v[220:221], 0, s[38:39]
	v_lshl_add_u64 v[54:55], v[222:223], 0, s[38:39]
	s_lshl_b64 s[90:91], s[36:37], 13
	v_lshl_add_u64 v[216:217], v[226:227], 0, s[90:91]
	v_mov_b32_e32 v124, v50
	v_mov_b32_e32 v125, v50
	v_mov_b32_e32 v126, v50
	v_mov_b32_e32 v127, v50
	v_mov_b32_e32 v112, v50
	v_mov_b32_e32 v113, v50
	v_mov_b32_e32 v114, v50
	v_mov_b32_e32 v115, v50
	s_and_b32 s38, s58, 1
	v_lshl_or_b32 v18, s38, 12, v238
	v_lshl_add_u32 v19, s38, 10, v239
	v_cmp_lt_i32_e32 vcc, 0, v240
	v_add_u32_e32 v19, 0, v19
	v_add_u32_e32 v18, 0, v18
	ds_read_b128 v[200:203], v19
	ds_read_b128 v[196:199], v19 offset:32
	ds_read_b128 v[192:195], v18
	ds_read_b128 v[188:191], v18 offset:1024
	ds_read_b128 v[184:187], v18 offset:2048
	ds_read_b128 v[180:183], v18 offset:3072
	ds_read_b128 v[204:207], v19 offset:64
	ds_read_b128 v[208:211], v19 offset:96
	s_waitcnt lgkmcnt(5)
	v_mov_b64_e32 v[214:215], v[194:195]
	v_mov_b64_e32 v[212:213], v[192:193]
	s_and_saveexec_b64 s[34:35], vcc
	s_cbranch_execz .Lscp0_b_550
	v_cmp_ne_u32_e32 vcc, 1, v240
	s_and_saveexec_b64 s[36:37], vcc
	s_xor_b64 s[36:37], exec, s[36:37]
	s_cbranch_execz .Lscp0_b_547
	s_waitcnt lgkmcnt(2)
	v_cndmask_b32_e64 v215, v183, v187, s[12:13]
	v_cndmask_b32_e64 v214, v182, v186, s[12:13]
	v_cndmask_b32_e64 v213, v181, v185, s[12:13]
	v_cndmask_b32_e64 v212, v180, v184, s[12:13]

; #define LAS __attribute__((address_space(3)))
; DI void scan_load(ScanFrags& F, const unsigned char* ws, int c, int h, int dir, int sl, int w, int lane) {
;     ...
;         for (int s = 0; s < 2; ++s) F.qa[mb][s] = *(const bf16x8*)(QT + ((w * 2 + mb) * 2 + s) * 512);
; #pragma unroll
;     for (int s = 0; s < 4; ++s) F.ka[s] = *(const bf16x8*)(KH + (w * 4 + s) * 512);
; #pragma unroll
;     for (int mb = 0; mb < 2; ++mb) F.aa[mb] = w < 4 ? *(const bf16x8*)(AM + ((w * 2 + mb)) * 512) : (bf16x8){0, 0, 0, 0, 0, 0, 0, 0};
; DI void phase_scan(const Params& p, LAS unsigned char* lds, unsigned char* ldsg, int j, int conv_rows, int next_layer) {
;     ...
;             const bf16x8 sb0 = pack8(S, 0), sb1 = pack8(S, 1);
;             bf16x8 vb[4]; f32x4 dd[4];
;             {
;                 unsigned vo = (unsigned)(SCAN_VB_OFF + (n & 1) * 4096 + lane * 16), dofs = (unsigned)(SCAN_DD_OFF + (n & 1) * 1024 + (32 * w + 4 * hh) * 4);
;                 asm volatile("" : "+v"(vo), "+v"(dofs));
; #pragma unroll
;                 for (int s = 0; s < 4; ++s) { vb[s] = *(const LAS bf16x8*)(lds + vo + s * 1024); dd[s] = *(const LAS f32x4*)(lds + dofs + s * 32); }
;             }
;             const bf16x8 vw = (w & 3) == 0 ? vb[0] : ((w & 3) == 1 ? vb[1] : ((w & 3) == 2 ? vb[2] : vb[3]));
;             bf16x8 aa0 = cur.aa[0], aa1 = cur.aa[1];
;             unsigned rbo = (unsigned)(((n & 1) * 8 + w) * 4608 + r * 72 + hh * 8);
;             asm volatile("" : "+v"(rbo));
;             LAS unsigned char* rb = lds + rbo;
; #pragma unroll
;             for (int mb = 0; mb < 2; ++mb) {
;                 f32x16 o;
; #pragma unroll
;                 for (int i = 0; i < 16; ++i) o[i] = 0.f;
;                 o = __builtin_amdgcn_mfma_f32_32x32x16_bf16(sb0, cur.qa[mb][0], o, 0, 0, 0);
;                 o = __builtin_amdgcn_mfma_f32_32x32x16_bf16(sb1, cur.qa[mb][1], o, 0, 0, 0);
;                 o = __builtin_amdgcn_mfma_f32_32x32x16_bf16(vw, mb ? aa1 : aa0, o, 0, 0, 0);
.Lw1b_p0b:
	v_cvt_pk_bf16_f32 v34, v2, v3
	v_cvt_pk_bf16_f32 v35, v4, v5
	v_cvt_pk_bf16_f32 v36, v6, v7
	v_cvt_pk_bf16_f32 v37, v8, v9
	v_cvt_pk_bf16_f32 v250, v10, v11
	v_cvt_pk_bf16_f32 v251, v12, v13
	v_mfma_f32_32x32x16_bf16 v[18:33], v[34:37], v[80:83], 0
	v_cvt_pk_bf16_f32 v252, v14, v15
	v_cvt_pk_bf16_f32 v253, v16, v17
	v_lshl_add_u32 v51, s38, 3, v1
	v_mad_u32_u24 v51, v51, s51, v241
	s_and_b32 s39, s57, 1
	v_add_u32_e32 v51, 0, v51
	v_mfma_f32_32x32x16_bf16 v[34:49], v[34:37], v[128:131], 0
	v_mfma_f32_32x32x16_bf16 v[18:33], v[250:253], v[88:91], v[18:33]
	v_mfma_f32_32x32x16_bf16 v[34:49], v[250:253], v[96:99], v[34:49]
	v_mfma_f32_32x32x16_bf16 v[18:33], v[212:215], v[176:179], v[18:33]
	v_mfma_f32_32x32x16_bf16 v[34:49], v[212:215], v[168:171], v[34:49]
	global_load_dwordx4 v[120:123], v[52:53], off
	global_load_dwordx4 v[116:119], v[52:53], off offset:1024
	global_load_dwordx4 v[108:111], v[52:53], off offset:2048
	global_load_dwordx4 v[104:107], v[52:53], off offset:3072
	s_and_saveexec_b64 s[92:93], s[4:5]
	s_cbranch_execz .Laask_p0b
	global_load_dwordx4 v[124:127], v[216:217], off
	global_load_dwordx4 v[112:115], v[216:217], off offset:1024

; #define LAS __attribute__((address_space(3)))
; DI void scan_load(ScanFrags& F, const unsigned char* ws, int c, int h, int dir, int sl, int w, int lane) {
;     const size_t blk = (size_t)((c * 4 + h) * 2 + dir);
;     const bf16_t* QT = (const bf16_t*)(ws + WS_U) + blk * 16384 + lane * 8;
;     const bf16_t* KH = (const bf16_t*)(ws + WS_KH) + blk * 16384 + lane * 8;
;     const bf16_t* AM = (const bf16_t*)(ws + WS_AM) + blk * 4096 + lane * 8;
; #pragma unroll
;     for (int mb = 0; mb < 2; ++mb)
; #pragma unroll
;         for (int s = 0; s < 2; ++s) F.qa[mb][s] = *(const bf16x8*)(QT + ((w * 2 + mb) * 2 + s) * 512);
; #pragma unroll
;     for (int s = 0; s < 4; ++s) F.ka[s] = *(const bf16x8*)(KH + (w * 4 + s) * 512);
; #pragma unroll
;     for (int mb = 0; mb < 2; ++mb) F.aa[mb] = w < 4 ? *(const bf16x8*)(AM + ((w * 2 + mb)) * 512) : (bf16x8){0, 0, 0, 0, 0, 0, 0, 0};
; DI void phase_scan(const Params& p, LAS unsigned char* lds, unsigned char* ldsg, int j, int conv_rows, int next_layer) {
;     ...
;             const int c = scan_chunk(n, b, dir);
;             scan_load(nn, p.ws, scan_chunk(n < 258 ? n + 2 : 259, b, dir), h, dir, sl, w, lane);
;             const bf16x8 sb0 = pack8(S, 0), sb1 = pack8(S, 1);
;             bf16x8 vb[4]; f32x4 dd[4];
;             {
;                 unsigned vo = (unsigned)(SCAN_VB_OFF + (n & 1) * 4096 + lane * 16), dofs = (unsigned)(SCAN_DD_OFF + (n & 1) * 1024 + (32 * w + 4 * hh) * 4);
;                 asm volatile("" : "+v"(vo), "+v"(dofs));
; #pragma unroll
;                 for (int s = 0; s < 4; ++s) { vb[s] = *(const LAS bf16x8*)(lds + vo + s * 1024); dd[s] = *(const LAS f32x4*)(lds + dofs + s * 32); }
;             }
;             const bf16x8 vw = (w & 3) == 0 ? vb[0] : ((w & 3) == 1 ? vb[1] : ((w & 3) == 2 ? vb[2] : vb[3]));
.Lscp0_top_c:
	s_add_i32 s58, s57, -1
	s_min_u32 s34, s58, 0x101
	s_add_i32 s36, s34, -2
	s_sub_i32 s37, 0x101, s34
	s_and_b64 s[34:35], s[30:31], exec
	s_cselect_b32 s34, s36, s37
	s_add_i32 s34, s34, s56
	s_lshl_b32 s34, s34, 2
	s_or_b32 s34, s34, s54
	s_mov_b32 s88, s34
	s_ashr_i32 s89, s34, 31
	s_lshl_b64 s[88:89], s[88:89], 15
	s_lshl_b32 s35, s34, 1
	s_or_b32 s36, s35, s55
	s_ashr_i32 s37, s36, 31
	s_lshl_b64 s[86:87], s[36:37], 10
	s_lshl_b64 s[38:39], s[36:37], 15
	v_lshl_add_u64 v[52:53], v[220:221], 0, s[38:39]
	v_lshl_add_u64 v[54:55], v[222:223], 0, s[38:39]
	s_lshl_b64 s[90:91], s[36:37], 13
	v_lshl_add_u64 v[216:217], v[226:227], 0, s[90:91]
	v_mov_b32_e32 v176, v50
	v_mov_b32_e32 v177, v50
	v_mov_b32_e32 v178, v50
	v_mov_b32_e32 v179, v50
	v_mov_b32_e32 v168, v50
	v_mov_b32_e32 v169, v50
	v_mov_b32_e32 v170, v50
	v_mov_b32_e32 v171, v50
	s_and_b32 s38, s58, 1
	v_lshl_or_b32 v18, s38, 12, v238
	v_lshl_add_u32 v19, s38, 10, v239
	v_cmp_lt_i32_e32 vcc, 0, v240
	v_add_u32_e32 v19, 0, v19
	v_add_u32_e32 v18, 0, v18
	ds_read_b128 v[200:203], v19
	ds_read_b128 v[196:199], v19 offset:32
	ds_read_b128 v[192:195], v18
	ds_read_b128 v[188:191], v18 offset:1024
	ds_read_b128 v[184:187], v18 offset:2048
	ds_read_b128 v[180:183], v18 offset:3072
	ds_read_b128 v[204:207], v19 offset:64
	ds_read_b128 v[208:211], v19 offset:96
	s_waitcnt lgkmcnt(5)
	v_mov_b64_e32 v[214:215], v[194:195]
	v_mov_b64_e32 v[212:213], v[192:193]
	s_and_saveexec_b64 s[34:35], vcc
	s_cbranch_execz .Lscp0_c_550
	v_cmp_ne_u32_e32 vcc, 1, v240
	s_and_saveexec_b64 s[36:37], vcc
	s_xor_b64 s[36:37], exec, s[36:37]
	s_cbranch_execz .Lscp0_c_547
	s_waitcnt lgkmcnt(2)
	v_cndmask_b32_e64 v215, v183, v187, s[12:13]
	v_cndmask_b32_e64 v214, v182, v186, s[12:13]
	v_cndmask_b32_e64 v213, v181, v185, s[12:13]
	v_cndmask_b32_e64 v212, v180, v184, s[12:13]

; #define LAS __attribute__((address_space(3)))
; DI void scan_load(ScanFrags& F, const unsigned char* ws, int c, int h, int dir, int sl, int w, int lane) {
;     ...
;         for (int s = 0; s < 2; ++s) F.qa[mb][s] = *(const bf16x8*)(QT + ((w * 2 + mb) * 2 + s) * 512);
; #pragma unroll
;     for (int s = 0; s < 4; ++s) F.ka[s] = *(const bf16x8*)(KH + (w * 4 + s) * 512);
; #pragma unroll
;     for (int mb = 0; mb < 2; ++mb) F.aa[mb] = w < 4 ? *(const bf16x8*)(AM + ((w * 2 + mb)) * 512) : (bf16x8){0, 0, 0, 0, 0, 0, 0, 0};
; DI void phase_scan(const Params& p, LAS unsigned char* lds, unsigned char* ldsg, int j, int conv_rows, int next_layer) {
;     ...
;             const bf16x8 sb0 = pack8(S, 0), sb1 = pack8(S, 1);
;             bf16x8 vb[4]; f32x4 dd[4];
;             {
;                 unsigned vo = (unsigned)(SCAN_VB_OFF + (n & 1) * 4096 + lane * 16), dofs = (unsigned)(SCAN_DD_OFF + (n & 1) * 1024 + (32 * w + 4 * hh) * 4);
;                 asm volatile("" : "+v"(vo), "+v"(dofs));
; #pragma unroll
;                 for (int s = 0; s < 4; ++s) { vb[s] = *(const LAS bf16x8*)(lds + vo + s * 1024); dd[s] = *(const LAS f32x4*)(lds + dofs + s * 32); }
;             }
;             const bf16x8 vw = (w & 3) == 0 ? vb[0] : ((w & 3) == 1 ? vb[1] : ((w & 3) == 2 ? vb[2] : vb[3]));
;             bf16x8 aa0 = cur.aa[0], aa1 = cur.aa[1];
;             unsigned rbo = (unsigned)(((n & 1) * 8 + w) * 4608 + r * 72 + hh * 8);
;             asm volatile("" : "+v"(rbo));
;             LAS unsigned char* rb = lds + rbo;
; #pragma unroll
;             for (int mb = 0; mb < 2; ++mb) {
;                 f32x16 o;
; #pragma unroll
;                 for (int i = 0; i < 16; ++i) o[i] = 0.f;
;                 o = __builtin_amdgcn_mfma_f32_32x32x16_bf16(sb0, cur.qa[mb][0], o, 0, 0, 0);
;                 o = __builtin_amdgcn_mfma_f32_32x32x16_bf16(sb1, cur.qa[mb][1], o, 0, 0, 0);
;                 o = __builtin_amdgcn_mfma_f32_32x32x16_bf16(vw, mb ? aa1 : aa0, o, 0, 0, 0);
.Lw1b_p0c:
	v_cvt_pk_bf16_f32 v34, v2, v3
	v_cvt_pk_bf16_f32 v35, v4, v5
	v_cvt_pk_bf16_f32 v36, v6, v7
	v_cvt_pk_bf16_f32 v37, v8, v9
	v_cvt_pk_bf16_f32 v250, v10, v11
	v_cvt_pk_bf16_f32 v251, v12, v13
	v_mfma_f32_32x32x16_bf16 v[18:33], v[34:37], v[76:79], 0
	v_cvt_pk_bf16_f32 v252, v14, v15
	v_cvt_pk_bf16_f32 v253, v16, v17
	v_lshl_add_u32 v51, s38, 3, v1
	v_mad_u32_u24 v51, v51, s51, v241
	s_and_b32 s39, s57, 1
	v_add_u32_e32 v51, 0, v51
	v_mfma_f32_32x32x16_bf16 v[34:49], v[34:37], v[92:95], 0
	v_mfma_f32_32x32x16_bf16 v[18:33], v[250:253], v[84:87], v[18:33]
	v_mfma_f32_32x32x16_bf16 v[34:49], v[250:253], v[100:103], v[34:49]
	v_mfma_f32_32x32x16_bf16 v[18:33], v[212:215], v[164:167], v[18:33]
	v_mfma_f32_32x32x16_bf16 v[34:49], v[212:215], v[172:175], v[34:49]
	global_load_dwordx4 v[80:83], v[52:53], off
	global_load_dwordx4 v[88:91], v[52:53], off offset:1024
	global_load_dwordx4 v[128:131], v[52:53], off offset:2048
	global_load_dwordx4 v[96:99], v[52:53], off offset:3072
	s_and_saveexec_b64 s[92:93], s[4:5]
	s_cbranch_execz .Laask_p0c
	global_load_dwordx4 v[176:179], v[216:217], off
	global_load_dwordx4 v[168:171], v[216:217], off offset:1024
